# v30: v29 + P3 odd workgroups run their sample-row tail tile after their GEMM tiles (even: before): desynchronises the gate-heavy epilogues of the two grid halves
# speedup vs baseline: 1.0232x; 1.0113x over previous
; #define LAS __attribute__((address_space(3)))
; __device__ __forceinline__ int permrow(int n) { return (n & ~255) | ((((n >> 5) & 1) * 128) + (((n >> 6) & 3) * 32) + (n & 31)); }
; template <int KSTEPS>
; __device__ __forceinline__ void tail_partial(const bf16_t* A, int lda, const bf16_t* Bt, int ldb, int col0, LAS float* part, int lane) {
;     const int fr = lane & 15, fq = lane >> 4;
;     f32x4 acc[2][4];
; #pragma unroll
;     for (int m = 0; m < 2; ++m)
; #pragma unroll
;         for (int n = 0; n < 4; ++n) acc[m][n] = (f32x4){0.f, 0.f, 0.f, 0.f};
;     const bf16_t* ap = A + (size_t)fr * lda + 8 * fq;
;     const bf16_t* bp[4];
; #pragma unroll
;     for (int n = 0; n < 4; ++n) bp[n] = Bt + (size_t)permrow(col0 + 16 * n + fr) * ldb + 8 * fq;
; #pragma unroll
;     for (int ks = 0; ks < KSTEPS; ++ks) {
;         bf16x8 a[2], b[4];
; #pragma unroll
;         for (int m = 0; m < 2; ++m) a[m] = *(const bf16x8*)(ap + (size_t)(16 * m) * lda + 32 * ks);
; #pragma unroll
;         for (int n = 0; n < 4; ++n) b[n] = *(const bf16x8*)(bp[n] + 32 * ks);
; __global__ void __launch_bounds__(NWAVES * 64, 2) fwd_megakernel(Args args) {
;     ...
;             const int tm = bx >> 4, tn = bx & 15, row0 = MP + 32 * tm, col0 = 64 * tn, br = wave >> 2, kw = (wave & 3) * 128;
;             LAS float* parts = (LAS float*)lds;
;             tail_partial<4>(U + (size_t)row0 * LDU + (br ? C_QB : C_QA) + kw, LDU, WO_t + br * 512 + kw, DM, col0, parts + wave * 2048, lane);
.LBB0_710:
	s_or_b64 exec, exec, s[0:1]
	v_readlane_b32 s2, v254, 19
	s_lshl_b32 s92, s94, 1
	v_readlane_b32 s3, v254, 20
	s_andn2_b32 s92, s92, 31
	s_lshl_b32 s23, s94, 6
	s_waitcnt lgkmcnt(0)
	v_cndmask_b32_e64 v1, 0, 1, s[2:3]
	s_mov_b32 s0, 0x8000
	s_add_i32 s84, s92, 0x8000
	s_and_b32 s22, s23, 0x3c0
	v_cmp_ne_u32_e64 s[38:39], 1, v1
	s_andn2_b64 vcc, exec, s[2:3]
	s_movk_i32 s85, 0x82
	s_barrier
	s_cbranch_vccnz .LBB0_712
	s_mov_b32 s40, 0
	s_bitcmp1_b32 s94, 0
	s_cbranch_scc0 .Lp3_tail
	s_movk_i32 s85, 0x80
	s_branch .LBB0_712
.Lp3_tail:
	s_lshr_b32 s10, s23, 1
	s_and_b32 s11, s10, 0x60
	s_mul_i32 s10, s84, 0x2a00
	v_mov_b32_e32 v40, v0
	s_mul_hi_i32 s12, s84, 0x2a00
	s_add_u32 s13, s82, s10
	s_addc_u32 s10, s83, s12
	v_readfirstlane_b32 s12, v40
	s_ashr_i32 s14, s12, 6
	s_cmpk_lt_u32 s12, 0x100
	s_cselect_b32 s15, 0, 0xa00
	s_add_u32 s16, s13, s15
	s_addc_u32 s13, s10, 0
	s_lshl_b32 s10, s14, 8
	s_and_b32 s14, s10, 0x300
	s_add_u32 s18, s16, s14
	s_addc_u32 s19, s13, 0
	s_lshl_b32 s10, s12, 1
	s_and_b32 s12, s10, 0xfffffe00
	s_ashr_i32 s13, s12, 31
	s_lshl_b64 s[16:17], s[12:13], 1
	s_add_u32 s10, s8, s16
	s_addc_u32 s12, s9, s17
	s_add_u32 s16, s10, s14
	v_and_b32_e32 v41, 15, v40
	s_addc_u32 s17, s12, 0
	v_mul_u32_u24_e32 v42, 0x1500, v41
	v_and_b32_e32 v44, 48, v40
	v_mov_b32_e32 v45, 0
	v_lshl_add_u64 v[50:51], s[16:17], 0, v[44:45]
	s_and_b32 s10, s23, 0x300
	v_lshlrev_b32_e32 v52, 1, v42
	v_mov_b32_e32 v53, v45
	s_or_b32 s12, s10, s11
	v_lshl_add_u64 v[42:43], s[18:19], 0, v[52:53]
	v_or_b32_e32 v52, s12, v41
	v_lshl_add_u64 v[58:59], v[42:43], 0, v[44:45]
	s_mov_b32 s10, 0x2a000
	v_lshlrev_b32_e32 v42, 11, v52
	v_mov_b32_e32 v43, v45
	v_add_co_u32_e32 v52, vcc, s10, v58
	s_nop 1
	v_lshl_add_u64 v[60:61], v[50:51], 0, v[42:43]
	v_addc_co_u32_e32 v53, vcc, 0, v59, vcc
	s_nop 1
	v_add_co_u32_e32 v42, vcc, s0, v60
	s_nop 1
	s_mov_b32 s10, 0x40000
	v_addc_co_u32_e32 v43, vcc, 0, v61, vcc
	s_nop 1
	v_add_co_u32_e32 v50, vcc, s10, v60
	s_nop 1
	global_load_dwordx4 v[64:67], v[60:61], off
	global_load_dwordx4 v[68:71], v[60:61], off offset:64
	v_addc_co_u32_e32 v51, vcc, 0, v61, vcc
	s_nop 1
	global_load_dwordx4 v[72:75], v[52:53], off
	global_load_dwordx4 v[84:87], v[42:43], off
	global_load_dwordx4 v[88:91], v[50:51], off
	s_mov_b32 s10, 0x48000
	v_add_co_u32_e32 v62, vcc, s10, v60
	s_nop 1
	global_load_dwordx4 v[92:95], v[58:59], off
	global_load_dwordx4 v[96:99], v[58:59], off offset:64
	v_addc_co_u32_e32 v63, vcc, 0, v61, vcc
	s_nop 1
	global_load_dwordx4 v[100:103], v[62:63], off
	global_load_dwordx4 v[104:107], v[52:53], off offset:64
	global_load_dwordx4 v[108:111], v[42:43], off offset:64
	global_load_dwordx4 v[112:115], v[50:51], off offset:64
	global_load_dwordx4 v[116:119], v[62:63], off offset:64
	s_movk_i32 s10, 0x2a00
	global_load_dwordx4 v[120:123], v[60:61], off offset:128
	global_load_dwordx4 v[124:127], v[58:59], off offset:128
	global_load_dwordx4 v[128:131], v[52:53], off offset:128
	global_load_dwordx4 v[132:135], v[42:43], off offset:128
	global_load_dwordx4 v[136:139], v[50:51], off offset:128
	global_load_dwordx4 v[140:143], v[58:59], off offset:192
	global_load_dwordx4 v[144:147], v[60:61], off offset:192
	global_load_dwordx4 v[148:151], v[62:63], off offset:128
	global_load_dwordx4 v[152:155], v[52:53], off offset:192
	global_load_dwordx4 v[156:159], v[62:63], off offset:192
	global_load_dwordx4 v[60:63], v[42:43], off offset:192
	global_load_dwordx4 v[160:163], v[50:51], off offset:192
	v_ashrrev_i32_e32 v41, 4, v40
	v_lshlrev_b32_e32 v42, 2, v40
	v_add_u32_e32 v40, s84, v41
	v_and_or_b32 v41, v42, 60, s22
	v_mov_b64_e32 v[42:43], s[82:83]
	v_mad_i64_i32 v[50:51], s[12:13], v40, s10, v[42:43]
	v_lshlrev_b32_e32 v40, 1, v41
	v_mov_b32_e32 v42, v40
	v_mov_b32_e32 v43, v45
	v_lshl_add_u64 v[52:53], v[50:51], 0, v[42:43]
	s_movk_i32 s10, 0x1000
	v_add_co_u32_e32 v40, vcc, s10, v52
	s_nop 1
	s_movk_i32 s10, 0x2000
	v_addc_co_u32_e32 v41, vcc, 0, v53, vcc
	s_nop 1
	v_add_co_u32_e32 v42, vcc, s10, v52
	s_nop 1
	v_addc_co_u32_e32 v43, vcc, 0, v53, vcc
	s_nop 1
	global_load_dwordx2 v[44:45], v[40:41], off offset:2560
	global_load_dwordx2 v[40:41], v[42:43], off offset:512
	s_nop 0
	s_nop 0
	s_nop 0
	v_mov_b32_e32 v1, v0
	s_nop 0
	s_nop 0
	s_nop 0
	v_readfirstlane_b32 s4, v1
	s_ashr_i32 s6, s4, 6
	s_nop 0
	s_nop 0
	s_nop 0
	s_nop 0
	s_nop 0
	s_nop 0
	s_nop 0
	s_nop 0
	s_nop 0
	s_nop 0
	s_nop 0
	s_nop 0
	s_nop 0
	s_nop 0
	s_nop 0
	v_and_b32_e32 v80, 15, v1
	s_nop 0
	s_nop 0
	v_and_b32_e32 v78, 48, v1
	v_mov_b32_e32 v79, 0
	s_nop 0
	s_nop 0
	s_nop 0
	s_nop 0
	s_nop 0
	s_nop 0
	s_nop 0
	s_nop 0
	s_nop 0
	s_nop 0
	s_nop 0
	s_nop 0
	s_nop 0
	s_nop 0
	s_nop 0
	s_nop 0
	s_nop 0
	s_nop 0
	s_nop 0
	s_nop 0
	s_nop 0
	s_nop 0
	s_nop 0
	s_nop 0
	s_nop 0
	s_nop 0
	s_nop 0
	s_nop 0
	s_nop 0
	s_nop 0
	s_nop 0
	s_nop 0
	s_nop 0
	s_nop 0
	s_nop 0
	s_nop 0
	s_lshl_b32 s1, s6, 13
	s_add_i32 s1, s1, 0
	s_nop 0
	s_movk_i32 s85, 0x80
	s_nop 0
	s_waitcnt vmcnt(20)
; #define LAS __attribute__((address_space(3)))
; __device__ __forceinline__ unsigned cvt_pk_bf16(float lo, float hi) { const f32x2_t v = {lo, hi}; const bf16x2_t b = __builtin_convertvector(v, bf16x2_t); return __builtin_bit_cast(unsigned, b); }
; __device__ __forceinline__ float bf_lo(unsigned w) { return __uint_as_float(w << 16); }
; template <int KSTEPS>
; __device__ __forceinline__ void tail_partial(const bf16_t* A, int lda, const bf16_t* Bt, int ldb, int col0, LAS float* part, int lane) {
;     ...
;     for (int ks = 0; ks < KSTEPS; ++ks) {
;         bf16x8 a[2], b[4];
; #pragma unroll
;         for (int m = 0; m < 2; ++m) a[m] = *(const bf16x8*)(ap + (size_t)(16 * m) * lda + 32 * ks);
; #pragma unroll
;         for (int n = 0; n < 4; ++n) b[n] = *(const bf16x8*)(bp[n] + 32 * ks);
; #pragma unroll
;         for (int m = 0; m < 2; ++m)
; #pragma unroll
;             for (int n = 0; n < 4; ++n) acc[m][n] = __builtin_amdgcn_mfma_f32_16x16x32_bf16(b[n], a[m], acc[m][n], 0, 0, 0);
;     }
; #pragma unroll
;     for (int m = 0; m < 2; ++m)
; #pragma unroll
;         for (int n = 0; n < 4; ++n) *(LAS f32x4*)(part + (16 * m + fr) * 64 + 16 * n + 4 * fq) = acc[m][n];
; }
; __device__ __forceinline__ f32x4 tail_sum(const LAS float* parts, int w0, int w1, int tid) {
;     f32x4 s = (f32x4){0.f, 0.f, 0.f, 0.f};
;     for (int w = w0; w < w1; ++w) s += *(const LAS f32x4*)(parts + w * 2048 + tid * 4);
; __global__ void __launch_bounds__(NWAVES * 64, 2) fwd_megakernel(Args args) {
;     ...
;             tail_partial<4>(U + (size_t)row0 * LDU + (br ? C_QB : C_QA) + kw, LDU, WO_t + br * 512 + kw, DM, col0, parts + wave * 2048, lane);
;             __syncthreads();
;             const f32x4 ca = tail_sum(parts, 0, 4, tid), cb = tail_sum(parts, 4, 8, tid);
;             const int r = row0 + (tid >> 4), c = col0 + (tid & 15) * 4;
;             const u32x2 ga = *(const u32x2*)(U + (size_t)r * LDU + C_GA + c), gb = *(const u32x2*)(U + (size_t)r * LDU + C_GB + c);
;             u32x2 w;
;             w.x = cvt_pk_bf16(bf_lo(ga.x) * ca[0] + bf_lo(gb.x) * cb[0], bf_hi(ga.x) * ca[1] + bf_hi(gb.x) * cb[1]);
;             w.y = cvt_pk_bf16(bf_lo(ga.y) * ca[2] + bf_lo(gb.y) * cb[2], bf_hi(ga.y) * ca[3] + bf_hi(gb.y) * cb[3]);
;             *(u32x2*)(R1 + (size_t)r * DM + c) = w;
;             __syncthreads();
	v_mfma_f32_16x16x32_bf16 v[30:33], v[64:67], v[92:95], 0
	v_mfma_f32_16x16x32_bf16 v[2:5], v[64:67], v[72:75], 0
	v_mfma_f32_16x16x32_bf16 v[46:49], v[84:87], v[92:95], 0
	v_mfma_f32_16x16x32_bf16 v[54:57], v[88:91], v[92:95], 0
	s_nop 0
	s_waitcnt vmcnt(18)
	v_mfma_f32_16x16x32_bf16 v[6:9], v[100:103], v[92:95], 0
	v_mfma_f32_16x16x32_bf16 v[14:17], v[84:87], v[72:75], 0
	v_mfma_f32_16x16x32_bf16 v[18:21], v[88:91], v[72:75], 0
	v_mfma_f32_16x16x32_bf16 v[10:13], v[100:103], v[72:75], 0
	v_mfma_f32_16x16x32_bf16 v[30:33], v[68:71], v[96:99], v[30:33]
	s_nop 0
	s_waitcnt vmcnt(17)
	v_mfma_f32_16x16x32_bf16 v[2:5], v[68:71], v[104:107], v[2:5]
	s_nop 0
	s_waitcnt vmcnt(16)
	v_mfma_f32_16x16x32_bf16 v[26:29], v[108:111], v[96:99], v[46:49]
	s_nop 0
	s_waitcnt vmcnt(15)
	v_mfma_f32_16x16x32_bf16 v[34:37], v[112:115], v[96:99], v[54:57]
	s_nop 0
	s_waitcnt vmcnt(14)
	v_mfma_f32_16x16x32_bf16 v[6:9], v[116:119], v[96:99], v[6:9]
	s_nop 0
	v_mfma_f32_16x16x32_bf16 v[14:17], v[108:111], v[104:107], v[14:17]
	s_nop 0
	s_nop 0
	v_mfma_f32_16x16x32_bf16 v[18:21], v[112:115], v[104:107], v[18:21]
	s_nop 0
	v_mfma_f32_16x16x32_bf16 v[10:13], v[116:119], v[104:107], v[10:13]
	s_nop 0
	s_nop 0
	s_nop 0
	s_nop 0
	s_nop 0
	s_nop 0
	s_nop 0
	s_nop 0
	s_waitcnt vmcnt(12)
	v_mfma_f32_16x16x32_bf16 v[30:33], v[120:123], v[124:127], v[30:33]
	s_nop 0
	s_nop 0
	s_waitcnt vmcnt(11)
	v_mfma_f32_16x16x32_bf16 v[2:5], v[120:123], v[128:131], v[2:5]
	s_nop 0
	s_nop 0
	s_nop 0
	s_nop 0
	s_waitcnt vmcnt(10)
	v_mfma_f32_16x16x32_bf16 v[26:29], v[132:135], v[124:127], v[26:29]
	s_nop 0
	s_waitcnt vmcnt(9)
	v_mfma_f32_16x16x32_bf16 v[34:37], v[136:139], v[124:127], v[34:37]
	s_nop 0
	s_waitcnt vmcnt(6)
	v_mfma_f32_16x16x32_bf16 v[6:9], v[148:151], v[124:127], v[6:9]
	v_mfma_f32_16x16x32_bf16 v[14:17], v[132:135], v[128:131], v[14:17]
	v_mfma_f32_16x16x32_bf16 v[18:21], v[136:139], v[128:131], v[18:21]
	v_lshlrev_b32_e32 v38, 8, v80
	v_mfma_f32_16x16x32_bf16 v[10:13], v[148:151], v[128:131], v[10:13]
	v_mfma_f32_16x16x32_bf16 v[30:33], v[144:147], v[140:143], v[30:33]
	s_nop 0
	s_waitcnt vmcnt(3)
	v_mfma_f32_16x16x32_bf16 v[26:29], v[60:63], v[140:143], v[26:29]
	s_nop 0
	s_waitcnt vmcnt(2)
	v_mfma_f32_16x16x32_bf16 v[34:37], v[160:163], v[140:143], v[34:37]
	v_mfma_f32_16x16x32_bf16 v[6:9], v[156:159], v[140:143], v[6:9]
	v_mfma_f32_16x16x32_bf16 v[2:5], v[144:147], v[152:155], v[2:5]
	v_mfma_f32_16x16x32_bf16 v[14:17], v[60:63], v[152:155], v[14:17]
	v_add3_u32 v22, s1, v38, v78
	ds_write_b128 v22, v[30:33]
	s_nop 0
	ds_write_b128 v22, v[26:29] offset:64
	s_nop 0
	ds_write_b128 v22, v[34:37] offset:128
	ds_write_b128 v22, v[6:9] offset:192
	ds_write_b128 v22, v[2:5] offset:4096
	ds_write_b128 v22, v[14:17] offset:4160
	v_mfma_f32_16x16x32_bf16 v[18:21], v[160:163], v[152:155], v[18:21]
	v_mfma_f32_16x16x32_bf16 v[2:5], v[156:159], v[152:155], v[10:13]
	s_nop 6
	ds_write_b128 v22, v[18:21] offset:4224
	ds_write_b128 v22, v[2:5] offset:4288
	v_ashrrev_i32_e32 v2, 4, v1
	v_lshlrev_b32_e32 v3, 2, v1
	v_add_u32_e32 v2, s84, v2
	v_and_or_b32 v3, v3, 60, s22
	s_nop 0
	s_nop 0
	v_lshlrev_b32_e32 v78, 1, v3
	s_nop 0
	s_nop 0
	s_nop 0
	s_nop 0
	s_nop 0
	s_nop 0
	s_nop 0
	s_waitcnt lgkmcnt(0)
	s_nop 0
	s_nop 0
	s_barrier
	s_nop 0
	s_nop 0
	v_ashrrev_i32_e32 v3, 31, v2
	v_lshlrev_b64 v[2:3], 11, v[2:3]
	v_lshl_add_u32 v1, v1, 4, 0
	v_lshl_add_u64 v[2:3], s[80:81], 0, v[2:3]
	v_lshl_add_u64 v[38:39], v[2:3], 0, v[78:79]
	ds_read_b128 v[2:5], v1
	ds_read_b128 v[6:9], v1 offset:8192
	ds_read_b128 v[10:13], v1 offset:32768
	ds_read_b128 v[14:17], v1 offset:16384
	ds_read_b128 v[18:21], v1 offset:24576
	ds_read_b128 v[22:25], v1 offset:40960
	ds_read_b128 v[26:29], v1 offset:49152
	ds_read_b128 v[30:33], v1 offset:57344
	s_waitcnt lgkmcnt(5)
	v_pk_add_f32 v[12:13], v[12:13], 0 op_sel_hi:[1,0]
	v_pk_add_f32 v[10:11], v[10:11], 0 op_sel_hi:[1,0]
	v_pk_add_f32 v[4:5], v[4:5], 0 op_sel_hi:[1,0]
	v_pk_add_f32 v[2:3], v[2:3], 0 op_sel_hi:[1,0]
	s_waitcnt lgkmcnt(2)
	v_pk_add_f32 v[12:13], v[12:13], v[24:25]
	v_pk_add_f32 v[10:11], v[10:11], v[22:23]
	v_pk_add_f32 v[4:5], v[4:5], v[8:9]
	v_pk_add_f32 v[2:3], v[2:3], v[6:7]
	s_waitcnt lgkmcnt(1)
	v_pk_add_f32 v[6:7], v[12:13], v[28:29]
	v_pk_add_f32 v[8:9], v[10:11], v[26:27]
	v_pk_add_f32 v[4:5], v[4:5], v[16:17]
	v_pk_add_f32 v[2:3], v[2:3], v[14:15]
	s_waitcnt lgkmcnt(0)
	v_pk_add_f32 v[6:7], v[6:7], v[32:33]
	v_pk_add_f32 v[8:9], v[8:9], v[30:31]
	v_pk_add_f32 v[4:5], v[4:5], v[20:21]
	v_pk_add_f32 v[2:3], v[2:3], v[18:19]
	s_nop 0
	s_waitcnt vmcnt(1)
	v_lshlrev_b32_e32 v10, 16, v44
	s_nop 0
	s_waitcnt vmcnt(0)
	v_lshlrev_b32_e32 v12, 16, v40
	v_and_b32_e32 v13, 0xffff0000, v40
	v_lshlrev_b32_e32 v16, 16, v41
	v_and_b32_e32 v17, 0xffff0000, v41
	v_and_b32_e32 v11, 0xffff0000, v44
	v_lshlrev_b32_e32 v14, 16, v45
	v_and_b32_e32 v15, 0xffff0000, v45
	v_pk_mul_f32 v[8:9], v[8:9], v[12:13]
	v_pk_mul_f32 v[6:7], v[6:7], v[16:17]
	v_pk_fma_f32 v[2:3], v[2:3], v[10:11], v[8:9]
	v_pk_fma_f32 v[4:5], v[4:5], v[14:15], v[6:7]
	v_cvt_pk_bf16_f32 v2, v2, v3
	v_cvt_pk_bf16_f32 v3, v4, v5
	global_store_dwordx2 v[38:39], v[2:3], off
	s_barrier
	s_cmp_eq_u32 s40, 1
	s_cbranch_scc1 .Lp3_ret

; #define LAS __attribute__((address_space(3)))
; #define PG8_WAIT_V(n) asm volatile("s_waitcnt vmcnt(" #n ")" ::: "memory")
; #define PG8_BAR __builtin_amdgcn_s_barrier()
; template <class Epi, int AC0, int BC0, int NT0, int AC1, int BC1, int NT1>
; __device__ __forceinline__ void gemm_phase(LAS unsigned char* lds, const Gemm g, const StaticOrder& S, const Epi& E, int tid) {
;     ...
;     PG8_WAIT_V(0);
;     PG8_BAR;
; __global__ void __launch_bounds__(NWAVES * 64, 2) fwd_megakernel(Args args) {
;     ...
;             const int tm = bx >> 4, tn = bx & 15, row0 = MP + 32 * tm, col0 = 64 * tn, br = wave >> 2, kw = (wave & 3) * 128;
;             LAS float* parts = (LAS float*)lds;
;             tail_partial<4>(U + (size_t)row0 * LDU + (br ? C_QB : C_QA) + kw, LDU, WO_t + br * 512 + kw, DM, col0, parts + wave * 2048, lane);
.LBB0_829:
	s_waitcnt vmcnt(0)
	v_readlane_b32 s94, v254, 10
	v_readlane_b32 s20, v254, 4
	v_readlane_b32 s95, v254, 11
	v_readlane_b32 s93, v254, 12
	v_readlane_b32 s21, v254, 5
	s_bitcmp1_b32 s94, 0
	s_cbranch_scc0 .Lp3_ret
	s_barrier
	s_mov_b32 s40, 1
	s_mov_b32 s0, 0x8000
	s_add_u32 s8, s62, 0xd00000
	s_addc_u32 s9, s63, 0
	s_branch .Lp3_tail
.Lp3_ret:
	s_barrier
